# NSA task finalization and s==cur accumulate: accb loads issued together instead of serialized load/wait chains
# baseline (speedup 1.0000x reference)
; __device__ __forceinline__ unsigned cvt_pk_bf16(float lo, float hi) { unsigned r; asm volatile("v_cvt_pk_bf16_f32 %0, %1, %2" : "=v"(r) : "v"(lo), "v"(hi)); return r; }
; __device__ __forceinline__ float x16sum(float x) { auto r = __builtin_amdgcn_permlane16_swap(__float_as_uint(x), __float_as_uint(x), false, false); return __uint_as_float(r[0]) + __uint_as_float(r[1]); }
; __device__ __forceinline__ float x32sum(float x) { auto r = __builtin_amdgcn_permlane32_swap(__float_as_uint(x), __float_as_uint(x), false, false); return __uint_as_float(r[0]) + __uint_as_float(r[1]); }
; __device__ __forceinline__ void nsa_wg_task(bf16_t* zb, const bf16_t* kcb, const bf16_t* vctb, const bf16_t* vst, const bf16_t* vwt, int g, int T0, float* accb, LAS unsigned char* lds, int wave, int lane, int tid) {
;     ...
;     asm volatile("s_waitcnt vmcnt(0)" ::: "memory"); __builtin_amdgcn_s_barrier(); asm volatile("" ::: "memory");
;     ...
; #pragma unroll
;     for (int r = 0; r < 2; ++r) { l[r] = x16sum(l[r]); l[r] = x32sum(l[r]);
;         const float sc = (l[r] > 0.f ? 1.0f / l[r] : 0.f) * gate_w[r];
; #pragma unroll
;         for (int dt = 0; dt < 4; ++dt) O[r][dt] = *(const f32x4*)(accb + (size_t)t[r] * 1024 + (g * 4 + h) * 64 + dt * 16 + 4 * fq) + O[r][dt] * sc;
;         bf16_t* op = zb + (size_t)t[r] * ZM + ZC_Q + (g * 4 + h) * 64 + 4 * fq;
; #pragma unroll
;         for (int dt = 0; dt < 4; ++dt) { u32x2 w; w.x = cvt_pk_bf16(O[r][dt][0], O[r][dt][1]); w.y = cvt_pk_bf16(O[r][dt][2], O[r][dt][3]); *(u32x2*)(op + dt * 16) = w; } }
.LBB0_148:
	s_waitcnt vmcnt(0)
	v_lshlrev_b32_e32 v0, 16, v190
	v_mul_f32_e32 v0, 0xbfb8aa3b, v0
	v_exp_f32_e32 v0, v0
	s_waitcnt vmcnt(0)
	s_barrier
	v_add_f32_e32 v0, 1.0, v0
	s_waitcnt lgkmcnt(0)
	v_rcp_f32_e32 v24, v0
	v_lshlrev_b32_e32 v0, 16, v188
	v_mul_f32_e32 v0, 0xbfb8aa3b, v0
	v_exp_f32_e32 v0, v0
	s_add_i32 s49, s49, s35
	s_cmpk_gt_i32 s49, 0x1ff
	v_add_f32_e32 v0, 1.0, v0
	v_rcp_f32_e32 v2, v0
	v_lshl_add_u64 v[0:1], v[170:171], 2, s[36:37]
	v_lshl_add_u64 v[4:5], v[166:167], 2, v[0:1]
	v_lshl_add_u64 v[222:223], v[4:5], 0, v[168:169]
	v_lshl_add_u64 v[224:225], v[4:5], 0, v[162:163]
	global_load_dwordx4 v[132:135], v[222:223], off
	global_load_dwordx4 v[136:139], v[222:223], off offset:64
	global_load_dwordx4 v[140:143], v[222:223], off offset:128
	global_load_dwordx4 v[144:147], v[222:223], off offset:192
	global_load_dwordx4 v[206:209], v[224:225], off
	global_load_dwordx4 v[210:213], v[224:225], off offset:64
	global_load_dwordx4 v[214:217], v[224:225], off offset:128
	global_load_dwordx4 v[218:221], v[224:225], off offset:192
	v_mov_b32_e32 v0, v172
	s_nop 1
	v_permlane16_swap_b32_e32 v172, v0
	v_add_f32_e32 v0, v172, v0
	v_mov_b32_e32 v1, v0
	s_nop 1
	v_permlane32_swap_b32_e32 v0, v1
	v_add_f32_e32 v0, v0, v1
	v_div_scale_f32 v1, s[0:1], v0, v0, 1.0
	v_rcp_f32_e32 v3, v1
	v_cmp_lt_f32_e64 s[4:5], 0, v0
	v_fma_f32 v6, -v1, v3, 1.0
	v_fmac_f32_e32 v3, v6, v3
	v_div_scale_f32 v6, vcc, 1.0, v0, 1.0
	v_mul_f32_e32 v7, v6, v3
	v_fma_f32 v8, -v1, v7, v6
	v_fmac_f32_e32 v7, v8, v3
	v_fma_f32 v1, -v1, v7, v6
	v_div_fmas_f32 v1, v1, v3, v7
	v_div_fixup_f32 v0, v1, v0, 1.0
	v_cndmask_b32_e64 v0, 0, v0, s[4:5]
	v_lshl_add_u64 v[8:9], v[4:5], 0, v[168:169]
	v_mul_f32_e32 v6, v2, v0
	v_lshl_add_u64 v[4:5], v[4:5], 0, v[162:163]
	s_waitcnt vmcnt(0)
	v_pk_fma_f32 v[10:11], v[114:115], v[6:7], v[134:135] op_sel_hi:[1,0,1]
	v_pk_fma_f32 v[12:13], v[112:113], v[6:7], v[132:133] op_sel_hi:[1,0,1]
	s_waitcnt vmcnt(0)
	v_pk_fma_f32 v[14:15], v[110:111], v[6:7], v[138:139] op_sel_hi:[1,0,1]
	v_pk_fma_f32 v[16:17], v[108:109], v[6:7], v[136:137] op_sel_hi:[1,0,1]
	s_waitcnt vmcnt(0)
	v_pk_fma_f32 v[18:19], v[106:107], v[6:7], v[142:143] op_sel_hi:[1,0,1]
	v_pk_fma_f32 v[20:21], v[104:105], v[6:7], v[140:141] op_sel_hi:[1,0,1]
	v_cvt_pk_bf16_f32 v12, v12, v13
	v_cvt_pk_bf16_f32 v13, v10, v11
	s_waitcnt vmcnt(0)
	v_pk_fma_f32 v[8:9], v[102:103], v[6:7], v[146:147] op_sel_hi:[1,0,1]
	v_pk_fma_f32 v[6:7], v[100:101], v[6:7], v[144:145] op_sel_hi:[1,0,1]
	v_lshlrev_b64 v[0:1], 1, v[170:171]
	v_lshl_add_u64 v[22:23], v[156:157], 0, v[0:1]
	v_lshlrev_b64 v[2:3], 1, v[166:167]
	v_lshl_add_u64 v[22:23], v[22:23], 0, v[2:3]
	global_store_dwordx2 v[22:23], v[12:13], off offset:2048
	v_cvt_pk_bf16_f32 v10, v16, v17
	v_cvt_pk_bf16_f32 v11, v14, v15
	global_store_dwordx2 v[22:23], v[10:11], off offset:2080
	v_cvt_pk_bf16_f32 v10, v20, v21
	v_cvt_pk_bf16_f32 v11, v18, v19
	global_store_dwordx2 v[22:23], v[10:11], off offset:2112
	v_cvt_pk_bf16_f32 v6, v6, v7
	v_cvt_pk_bf16_f32 v7, v8, v9
	global_store_dwordx2 v[22:23], v[6:7], off offset:2144
	v_mov_b32_e32 v6, v173
	s_nop 1
	v_permlane16_swap_b32_e32 v173, v6
	v_add_f32_e32 v6, v173, v6
	v_mov_b32_e32 v7, v6
	s_nop 1
	v_permlane32_swap_b32_e32 v6, v7
	v_add_f32_e32 v6, v6, v7
	v_div_scale_f32 v7, s[0:1], v6, v6, 1.0
	v_rcp_f32_e32 v8, v7
	v_cmp_lt_f32_e64 s[4:5], 0, v6
	v_lshl_add_u64 v[0:1], v[66:67], 0, v[0:1]
	v_lshl_add_u64 v[0:1], v[0:1], 0, v[2:3]
	v_fma_f32 v9, -v7, v8, 1.0
	v_fmac_f32_e32 v8, v9, v8
	v_div_scale_f32 v9, vcc, 1.0, v6, 1.0
	v_mul_f32_e32 v10, v9, v8
	v_fma_f32 v11, -v7, v10, v9
	v_fmac_f32_e32 v10, v11, v8
	v_fma_f32 v7, -v7, v10, v9
	v_div_fmas_f32 v7, v7, v8, v10
	v_div_fixup_f32 v6, v7, v6, 1.0
	v_cndmask_b32_e64 v6, 0, v6, s[4:5]
	v_mul_f32_e32 v6, v24, v6
	s_waitcnt vmcnt(0)
	v_pk_fma_f32 v[12:13], v[98:99], v[6:7], v[208:209] op_sel_hi:[1,0,1]
	v_pk_fma_f32 v[14:15], v[96:97], v[6:7], v[206:207] op_sel_hi:[1,0,1]
	s_waitcnt vmcnt(0)
	v_pk_fma_f32 v[16:17], v[94:95], v[6:7], v[212:213] op_sel_hi:[1,0,1]
	v_pk_fma_f32 v[18:19], v[92:93], v[6:7], v[210:211] op_sel_hi:[1,0,1]
	s_waitcnt vmcnt(0)
	v_pk_fma_f32 v[20:21], v[90:91], v[6:7], v[216:217] op_sel_hi:[1,0,1]
	v_pk_fma_f32 v[22:23], v[88:89], v[6:7], v[214:215] op_sel_hi:[1,0,1]
	v_cvt_pk_bf16_f32 v2, v14, v15
	v_cvt_pk_bf16_f32 v3, v12, v13
	global_store_dwordx2 v[0:1], v[2:3], off offset:2048
	v_cvt_pk_bf16_f32 v2, v18, v19
	v_cvt_pk_bf16_f32 v3, v16, v17
	global_store_dwordx2 v[0:1], v[2:3], off offset:2080
	v_cvt_pk_bf16_f32 v2, v22, v23
	v_cvt_pk_bf16_f32 v3, v20, v21
	global_store_dwordx2 v[0:1], v[2:3], off offset:2112
	s_waitcnt vmcnt(3)
	v_pk_fma_f32 v[4:5], v[86:87], v[6:7], v[220:221] op_sel_hi:[1,0,1]
	v_pk_fma_f32 v[6:7], v[84:85], v[6:7], v[218:219] op_sel_hi:[1,0,1]
	s_nop 0
	v_cvt_pk_bf16_f32 v2, v6, v7
	v_cvt_pk_bf16_f32 v3, v4, v5
	global_store_dwordx2 v[0:1], v[2:3], off offset:2144
	s_cbranch_scc1 .LBB0_351

; __device__ __forceinline__ float x16sum(float x) { auto r = __builtin_amdgcn_permlane16_swap(__float_as_uint(x), __float_as_uint(x), false, false); return __uint_as_float(r[0]) + __uint_as_float(r[1]); }
; __device__ __forceinline__ float x32sum(float x) { auto r = __builtin_amdgcn_permlane32_swap(__float_as_uint(x), __float_as_uint(x), false, false); return __uint_as_float(r[0]) + __uint_as_float(r[1]); }
; __device__ __forceinline__ void nsa_wg_task(bf16_t* zb, const bf16_t* kcb, const bf16_t* vctb, const bf16_t* vst, const bf16_t* vwt, int g, int T0, float* accb, LAS unsigned char* lds, int wave, int lane, int tid) {
;     ...
;             if (s == cur) {
; #pragma unroll
;                 for (int r = 0; r < 2; ++r) { l[r] = x16sum(l[r]); l[r] = x32sum(l[r]); const float sc = (l[r] > 0.f ? 1.0f / l[r] : 0.f) * gate_s[r];
; #pragma unroll
;                     for (int dt = 0; dt < 4; ++dt) { f32x4* ap = (f32x4*)(accb + (size_t)t[r] * 1024 + (g * 4 + h) * 64 + dt * 16 + 4 * fq); *ap = *ap + O[r][dt] * sc; O[r][dt] = zero4; }
;                     l[r] = 0.f; } }
.LBB0_237:
	s_cmp_lg_u32 s2, s61
	s_cbranch_scc1 .LBB0_239
	global_load_dwordx4 v[124:127], v[178:179], off
	global_load_dwordx4 v[128:131], v[178:179], off offset:64
	global_load_dwordx4 v[132:135], v[178:179], off offset:128
	global_load_dwordx4 v[136:139], v[178:179], off offset:192
	v_mov_b32_e32 v65, v186
	s_nop 1
	v_permlane16_swap_b32_e32 v186, v65
	v_add_f32_e32 v141, v186, v65
	v_mov_b32_e32 v65, v187
	s_nop 1
	v_permlane16_swap_b32_e32 v187, v65
	v_add_f32_e32 v140, v187, v65
	v_mov_b32_e32 v143, v141
	v_mov_b32_e32 v142, v140
	s_nop 0
	v_permlane32_swap_b32_e32 v141, v143
	v_permlane32_swap_b32_e32 v140, v142
	v_pk_add_f32 v[140:141], v[140:141], v[142:143]
	s_nop 0
	v_div_scale_f32 v65, s[20:21], v141, v141, 1.0
	v_rcp_f32_e32 v142, v65
	v_cmp_lt_f32_e64 s[20:21], 0, v140
	v_fma_f32 v143, -v65, v142, 1.0
	v_fmac_f32_e32 v142, v143, v142
	v_div_scale_f32 v143, vcc, 1.0, v141, 1.0
	v_mul_f32_e32 v144, v143, v142
	v_fma_f32 v145, -v65, v144, v143
	v_fmac_f32_e32 v144, v145, v142
	v_fma_f32 v65, -v65, v144, v143
	v_div_fmas_f32 v65, v65, v142, v144
	v_div_fixup_f32 v142, v65, v141, 1.0
	v_cmp_lt_f32_e32 vcc, 0, v141
	v_mov_b32_e32 v65, v64
	v_mov_b64_e32 v[186:187], v[64:65]
	v_cndmask_b32_e32 v141, 0, v142, vcc
	v_mul_f32_e32 v142, v159, v141
	s_waitcnt vmcnt(0)
	v_pk_fma_f32 v[122:123], v[122:123], v[142:143], v[126:127] op_sel_hi:[1,0,1]
	v_pk_fma_f32 v[120:121], v[120:121], v[142:143], v[124:125] op_sel_hi:[1,0,1]
	v_pk_fma_f32 v[54:55], v[54:55], v[142:143], v[134:135] op_sel_hi:[1,0,1]
	v_pk_fma_f32 v[50:51], v[50:51], v[142:143], v[138:139] op_sel_hi:[1,0,1]
	v_pk_fma_f32 v[48:49], v[48:49], v[142:143], v[136:137] op_sel_hi:[1,0,1]
	global_store_dwordx4 v[178:179], v[48:51], off offset:192
	v_pk_fma_f32 v[52:53], v[52:53], v[142:143], v[132:133] op_sel_hi:[1,0,1]
	global_store_dwordx4 v[178:179], v[52:55], off offset:128
	v_div_scale_f32 v48, s[22:23], v140, v140, 1.0
	v_rcp_f32_e32 v49, v48
	v_pk_fma_f32 v[118:119], v[118:119], v[142:143], v[130:131] op_sel_hi:[1,0,1]
	v_pk_fma_f32 v[116:117], v[116:117], v[142:143], v[128:129] op_sel_hi:[1,0,1]
	global_store_dwordx4 v[178:179], v[120:123], off
	v_fma_f32 v50, -v48, v49, 1.0
	v_fmac_f32_e32 v49, v50, v49
	v_div_scale_f32 v50, vcc, 1.0, v140, 1.0
	v_mul_f32_e32 v51, v50, v49
	v_fma_f32 v52, -v48, v51, v50
	v_fmac_f32_e32 v51, v52, v49
	v_fma_f32 v48, -v48, v51, v50
	v_div_fmas_f32 v48, v48, v49, v51
	global_load_dwordx4 v[50:53], v[180:181], off
	global_load_dwordx4 v[124:127], v[180:181], off offset:64
	global_load_dwordx4 v[128:131], v[180:181], off offset:128
	global_load_dwordx4 v[132:135], v[180:181], off offset:192
	v_div_fixup_f32 v48, v48, v140, 1.0
	v_cndmask_b32_e64 v48, 0, v48, s[20:21]
	v_mul_f32_e32 v48, v193, v48
	global_store_dwordx4 v[178:179], v[116:119], off offset:64
	s_waitcnt vmcnt(1)
	v_pk_fma_f32 v[46:47], v[46:47], v[48:49], v[52:53] op_sel_hi:[1,0,1]
	v_pk_fma_f32 v[44:45], v[44:45], v[48:49], v[50:51] op_sel_hi:[1,0,1]
	v_pk_fma_f32 v[42:43], v[42:43], v[48:49], v[126:127] op_sel_hi:[1,0,1]
	v_pk_fma_f32 v[40:41], v[40:41], v[48:49], v[124:125] op_sel_hi:[1,0,1]
	global_store_dwordx4 v[180:181], v[44:47], off
	v_pk_fma_f32 v[38:39], v[38:39], v[48:49], v[130:131] op_sel_hi:[1,0,1]
	v_pk_fma_f32 v[36:37], v[36:37], v[48:49], v[128:129] op_sel_hi:[1,0,1]
	global_store_dwordx4 v[180:181], v[40:43], off offset:64
	v_pk_fma_f32 v[34:35], v[34:35], v[48:49], v[134:135] op_sel_hi:[1,0,1]
	v_pk_fma_f32 v[32:33], v[32:33], v[48:49], v[132:133] op_sel_hi:[1,0,1]
	global_store_dwordx4 v[180:181], v[36:39], off offset:128
	v_mov_b64_e32 v[122:123], v[58:59]
	v_mov_b64_e32 v[120:121], v[56:57]
	global_store_dwordx4 v[180:181], v[32:35], off offset:192
	v_mov_b64_e32 v[118:119], v[58:59]
	v_mov_b64_e32 v[116:117], v[56:57]
	v_mov_b64_e32 v[52:53], v[56:57]
	v_mov_b64_e32 v[54:55], v[58:59]
	v_mov_b64_e32 v[44:45], v[56:57]
	v_mov_b64_e32 v[46:47], v[58:59]
	v_mov_b64_e32 v[40:41], v[56:57]
	v_mov_b64_e32 v[42:43], v[58:59]
	v_mov_b64_e32 v[36:37], v[56:57]
	v_mov_b64_e32 v[48:49], v[56:57]
	v_mov_b64_e32 v[32:33], v[56:57]
	v_mov_b64_e32 v[34:35], v[58:59]
	v_mov_b64_e32 v[38:39], v[58:59]
	v_mov_b64_e32 v[50:51], v[58:59]
